# conversion jobs of the down/out GEMM phases spread over all 256 workgroups (first_blk 16 -> 0)
# speedup vs baseline: 1.0071x; 1.0071x over previous
; __device__ void run_phase(const KP& p_, int ph) {
;     ...
;     else if (q == 7) { gemm_phase<2, DM, DM>(p, l, mix, Wl + W_OUT); if (l == 0) { plo = 5440; phi = 6140; } }
.LBB0_307:
	v_readlane_b32 s0, v255, 53
	v_readlane_b32 s1, v255, 54
	s_and_b64 s[0:1], s[0:1], exec
	s_cselect_b32 s33, 0x17fc, 0
	s_cselect_b32 s95, 0x1540, 0
	s_mov_b64 s[2:3], 0
	s_mov_b64 s[88:89], -1
	s_mov_b32 s67, 0

; __device__ void run_phase(const KP& p_, int ph) {
;     ...
;     else { gemm_phase<2, DM, DFF>(p, l, U, Wl + W_DB); if (l == 0) { plo = 6140; phi = 7552; } }
.LBB0_1137:
	v_readlane_b32 s0, v255, 53
	v_readlane_b32 s1, v255, 54
	s_and_b64 s[0:1], s[0:1], exec
	s_cselect_b32 s33, 0x1d80, 0
	s_cselect_b32 s95, 0x17fc, 0
	s_mov_b64 s[44:45], 0
	s_mov_b64 s[88:89], -1
	s_mov_b32 s67, 0

; __device__ void run_phase(const KP& p_, int ph) {
;     ...
;     else if (q == 1) { gemm_phase<2, DM, DFF>(p, l, U, Wl + W_DA); if (l == 0) { plo = 2112; phi = 5440; } else { plo = 7552; phi = 10880; } }
.LBB0_1167:
	v_readlane_b32 s0, v255, 53
	v_readlane_b32 s1, v255, 54
	s_and_b64 s[0:1], s[0:1], exec
	s_movk_i32 s0, 0x2a80
	s_cselect_b32 s33, 0x1540, s0
	s_movk_i32 s0, 0x840
	s_cselect_b32 s95, s0, 0x1d80
	s_mov_b64 s[0:1], 0
	v_writelane_b32 v255, s0, 62
	s_mov_b64 s[88:89], -1
	s_mov_b32 s67, 0
	v_writelane_b32 v255, s1, 63
	s_mov_b64 s[44:45], 0
	s_branch .LBB0_1125
